# grid barrier: non-leader workgroups poll the top-level generation word directly (one release hop removed); arrival unchanged
# speedup vs baseline: 1.0079x; 1.0079x over previous
; __device__ __forceinline__ unsigned xb_ld(unsigned* p)              { return __hip_atomic_load(p, __ATOMIC_RELAXED, __HIP_MEMORY_SCOPE_AGENT); }
; __device__ __forceinline__ unsigned xb_add(unsigned* p, unsigned v) { return __hip_atomic_fetch_add(p, v, __ATOMIC_RELAXED, __HIP_MEMORY_SCOPE_AGENT); }
; #define XB_SPIN(cond, bar) do { unsigned _sp = 0; while (cond) { __builtin_amdgcn_s_sleep(1); \
;     if ((++_sp & 255u) == 0u) { if (xb_ld(&(bar)[XB_TMO])) break; if (_sp > XB_SPIN_CAP) { atomicAdd(&(bar)[XB_TMO], 1u); break; } } } } while (0)
; __device__ __forceinline__ void xcd_barrier(const XcdBarrier& b) {
;     ...
;         const unsigned old = xb_add(&bar[XB_XSUB(b.x)], 1u);
;         const unsigned gen = old / nloc;
;         if (old + 1u == (gen + 1u) * nloc) {
;             __builtin_amdgcn_fence(__ATOMIC_RELEASE, "agent");
;             asm volatile("s_waitcnt vmcnt(0)" ::: "memory");
;             const unsigned og = xb_add(&bar[XB_TOP], 1u);
;             const unsigned tg = og / nx;
;             if (og + 1u == (tg + 1u) * nx) xb_add(&bar[XB_TOPGEN], 1u);
;             else XB_SPIN(xb_ld(&bar[XB_TOPGEN]) == tg, bar);
;             __builtin_amdgcn_fence(__ATOMIC_ACQUIRE, "agent");
;             xb_add(&bar[XB_XGEN(b.x)], 1u);
;             asm volatile("s_waitcnt vmcnt(0)" ::: "memory");
;         } else {
;             XB_SPIN(xb_ld(&bar[XB_XGEN(b.x)]) == gen, bar);
;             __builtin_amdgcn_fence(__ATOMIC_ACQUIRE, "agent");
.LBB0_51:
	s_or_b64 exec, exec, s[6:7]
	v_cvt_f32_u32_e32 v5, v3
	s_waitcnt vmcnt(0)
	v_readfirstlane_b32 s2, v4
	v_sub_u32_e32 v4, 0, v3
	v_rcp_iflag_f32_e32 v5, v5
	v_add_u32_e32 v6, s2, v2
	v_mul_f32_e32 v5, 0x4f7ffffe, v5
	v_cvt_u32_f32_e32 v5, v5
	v_mul_lo_u32 v2, v4, v5
	v_mul_hi_u32 v2, v5, v2
	v_add_u32_e32 v2, v5, v2
	v_mul_hi_u32 v2, v6, v2
	v_mul_lo_u32 v4, v2, v3
	v_sub_u32_e32 v4, v6, v4
	v_add_u32_e32 v5, 1, v2
	v_cmp_ge_u32_e32 vcc, v4, v3
	s_nop 1
	v_cndmask_b32_e32 v2, v2, v5, vcc
	v_sub_u32_e32 v5, v4, v3
	v_cndmask_b32_e32 v4, v4, v5, vcc
	v_add_u32_e32 v5, 1, v2
	v_cmp_ge_u32_e32 vcc, v4, v3
	v_add_u32_e32 v4, 1, v6
	s_nop 0
	v_cndmask_b32_e32 v2, v2, v5, vcc
	v_mul_lo_u32 v5, v3, v2
	v_add_u32_e32 v3, v5, v3
	v_cmp_ne_u32_e32 vcc, v4, v3
	s_and_saveexec_b64 s[2:3], vcc
	s_xor_b64 s[2:3], exec, s[2:3]
	s_cbranch_execz .LBB0_65
	s_waitcnt lgkmcnt(0)
	v_mov_b32_e32 v1, 0
	s_add_u32 s14, s54, 0x7500
	s_addc_u32 s15, s55, 0
	global_load_dword v1, v1, s[14:15] sc1
	s_waitcnt vmcnt(0)
	v_cmp_eq_u32_e32 vcc, v1, v2
	s_and_saveexec_b64 s[6:7], vcc
	s_cbranch_execz .LBB0_64
	s_add_u32 s12, s54, 0x4200
	s_addc_u32 s13, s55, 0
	s_mov_b32 s26, 1
	s_mov_b64 s[16:17], 0
	v_mov_b32_e32 v1, 0
	s_branch .LBB0_55

; __device__ __forceinline__ unsigned xb_ld(unsigned* p)              { return __hip_atomic_load(p, __ATOMIC_RELAXED, __HIP_MEMORY_SCOPE_AGENT); }
; __device__ __forceinline__ unsigned xb_add(unsigned* p, unsigned v) { return __hip_atomic_fetch_add(p, v, __ATOMIC_RELAXED, __HIP_MEMORY_SCOPE_AGENT); }
; #define XB_SPIN(cond, bar) do { unsigned _sp = 0; while (cond) { __builtin_amdgcn_s_sleep(1); \
;     if ((++_sp & 255u) == 0u) { if (xb_ld(&(bar)[XB_TMO])) break; if (_sp > XB_SPIN_CAP) { atomicAdd(&(bar)[XB_TMO], 1u); break; } } } } while (0)
; __device__ __forceinline__ void xcd_barrier(const XcdBarrier& b) {
;     ...
;         const unsigned old = xb_add(&bar[XB_XSUB(b.x)], 1u);
;         const unsigned gen = old / nloc;
;         if (old + 1u == (gen + 1u) * nloc) {
;             __builtin_amdgcn_fence(__ATOMIC_RELEASE, "agent");
;             asm volatile("s_waitcnt vmcnt(0)" ::: "memory");
;             const unsigned og = xb_add(&bar[XB_TOP], 1u);
;             const unsigned tg = og / nx;
;             if (og + 1u == (tg + 1u) * nx) xb_add(&bar[XB_TOPGEN], 1u);
;             else XB_SPIN(xb_ld(&bar[XB_TOPGEN]) == tg, bar);
;             __builtin_amdgcn_fence(__ATOMIC_ACQUIRE, "agent");
;             xb_add(&bar[XB_XGEN(b.x)], 1u);
;             asm volatile("s_waitcnt vmcnt(0)" ::: "memory");
;         } else {
;             XB_SPIN(xb_ld(&bar[XB_XGEN(b.x)]) == gen, bar);
;             __builtin_amdgcn_fence(__ATOMIC_ACQUIRE, "agent");
.LBB0_134:
	s_or_b64 exec, exec, s[6:7]
	v_cvt_f32_u32_e32 v5, v3
	s_waitcnt vmcnt(0)
	v_readfirstlane_b32 s2, v4
	v_sub_u32_e32 v4, 0, v3
	v_rcp_iflag_f32_e32 v5, v5
	v_add_u32_e32 v6, s2, v2
	v_mul_f32_e32 v5, 0x4f7ffffe, v5
	v_cvt_u32_f32_e32 v5, v5
	v_mul_lo_u32 v2, v4, v5
	v_mul_hi_u32 v2, v5, v2
	v_add_u32_e32 v2, v5, v2
	v_mul_hi_u32 v2, v6, v2
	v_mul_lo_u32 v4, v2, v3
	v_sub_u32_e32 v4, v6, v4
	v_add_u32_e32 v5, 1, v2
	v_cmp_ge_u32_e32 vcc, v4, v3
	s_nop 1
	v_cndmask_b32_e32 v2, v2, v5, vcc
	v_sub_u32_e32 v5, v4, v3
	v_cndmask_b32_e32 v4, v4, v5, vcc
	v_add_u32_e32 v5, 1, v2
	v_cmp_ge_u32_e32 vcc, v4, v3
	v_add_u32_e32 v4, 1, v6
	s_nop 0
	v_cndmask_b32_e32 v2, v2, v5, vcc
	v_mul_lo_u32 v5, v3, v2
	v_add_u32_e32 v3, v5, v3
	v_cmp_ne_u32_e32 vcc, v4, v3
	s_and_saveexec_b64 s[2:3], vcc
	s_xor_b64 s[2:3], exec, s[2:3]
	s_cbranch_execz .LBB0_148
	s_waitcnt lgkmcnt(0)
	v_mov_b32_e32 v1, 0
	s_add_u32 s12, s54, 0x7500
	s_addc_u32 s13, s55, 0
	global_load_dword v1, v1, s[12:13] sc1
	s_waitcnt vmcnt(0)
	v_cmp_eq_u32_e32 vcc, v1, v2
	s_and_saveexec_b64 s[6:7], vcc
	s_cbranch_execz .LBB0_147
	s_add_u32 s10, s54, 0x4200
	s_addc_u32 s11, s55, 0
	s_mov_b32 s26, 1
	s_mov_b64 s[14:15], 0
	v_mov_b32_e32 v1, 0
	s_branch .LBB0_138

; __device__ __forceinline__ unsigned xb_ld(unsigned* p)              { return __hip_atomic_load(p, __ATOMIC_RELAXED, __HIP_MEMORY_SCOPE_AGENT); }
; __device__ __forceinline__ unsigned xb_add(unsigned* p, unsigned v) { return __hip_atomic_fetch_add(p, v, __ATOMIC_RELAXED, __HIP_MEMORY_SCOPE_AGENT); }
; #define XB_SPIN(cond, bar) do { unsigned _sp = 0; while (cond) { __builtin_amdgcn_s_sleep(1); \
;     if ((++_sp & 255u) == 0u) { if (xb_ld(&(bar)[XB_TMO])) break; if (_sp > XB_SPIN_CAP) { atomicAdd(&(bar)[XB_TMO], 1u); break; } } } } while (0)
; __device__ __forceinline__ void xcd_barrier(const XcdBarrier& b) {
;     ...
;         const unsigned old = xb_add(&bar[XB_XSUB(b.x)], 1u);
;         const unsigned gen = old / nloc;
;         if (old + 1u == (gen + 1u) * nloc) {
;             __builtin_amdgcn_fence(__ATOMIC_RELEASE, "agent");
;             asm volatile("s_waitcnt vmcnt(0)" ::: "memory");
;             const unsigned og = xb_add(&bar[XB_TOP], 1u);
;             const unsigned tg = og / nx;
;             if (og + 1u == (tg + 1u) * nx) xb_add(&bar[XB_TOPGEN], 1u);
;             else XB_SPIN(xb_ld(&bar[XB_TOPGEN]) == tg, bar);
;             __builtin_amdgcn_fence(__ATOMIC_ACQUIRE, "agent");
;             xb_add(&bar[XB_XGEN(b.x)], 1u);
;             asm volatile("s_waitcnt vmcnt(0)" ::: "memory");
;         } else {
;             XB_SPIN(xb_ld(&bar[XB_XGEN(b.x)]) == gen, bar);
;             __builtin_amdgcn_fence(__ATOMIC_ACQUIRE, "agent");
.LBB0_281:
	s_or_b64 exec, exec, s[6:7]
	v_cvt_f32_u32_e32 v5, v3
	s_waitcnt vmcnt(0)
	v_readfirstlane_b32 s2, v4
	v_sub_u32_e32 v4, 0, v3
	v_rcp_iflag_f32_e32 v5, v5
	v_add_u32_e32 v6, s2, v2
	v_mul_f32_e32 v5, 0x4f7ffffe, v5
	v_cvt_u32_f32_e32 v5, v5
	v_mul_lo_u32 v2, v4, v5
	v_mul_hi_u32 v2, v5, v2
	v_add_u32_e32 v2, v5, v2
	v_mul_hi_u32 v2, v6, v2
	v_mul_lo_u32 v4, v2, v3
	v_sub_u32_e32 v4, v6, v4
	v_add_u32_e32 v5, 1, v2
	v_cmp_ge_u32_e32 vcc, v4, v3
	s_nop 1
	v_cndmask_b32_e32 v2, v2, v5, vcc
	v_sub_u32_e32 v5, v4, v3
	v_cndmask_b32_e32 v4, v4, v5, vcc
	v_add_u32_e32 v5, 1, v2
	v_cmp_ge_u32_e32 vcc, v4, v3
	v_add_u32_e32 v4, 1, v6
	s_nop 0
	v_cndmask_b32_e32 v2, v2, v5, vcc
	v_mul_lo_u32 v5, v3, v2
	v_add_u32_e32 v3, v5, v3
	v_cmp_ne_u32_e32 vcc, v4, v3
	s_and_saveexec_b64 s[2:3], vcc
	s_xor_b64 s[2:3], exec, s[2:3]
	s_cbranch_execz .LBB0_295
	s_waitcnt lgkmcnt(0)
	v_mov_b32_e32 v1, 0
	s_add_u32 s10, s54, 0x7500
	s_addc_u32 s11, s55, 0
	global_load_dword v1, v1, s[10:11] sc1
	s_waitcnt vmcnt(0)
	v_cmp_eq_u32_e32 vcc, v1, v2
	s_and_saveexec_b64 s[6:7], vcc
	s_cbranch_execz .LBB0_294
	s_add_u32 s8, s54, 0x4200
	s_addc_u32 s9, s55, 0
	s_mov_b32 s24, 1
	s_mov_b64 s[12:13], 0
	v_mov_b32_e32 v1, 0
	s_branch .LBB0_285

; __device__ __forceinline__ unsigned xb_ld(unsigned* p)              { return __hip_atomic_load(p, __ATOMIC_RELAXED, __HIP_MEMORY_SCOPE_AGENT); }
; __device__ __forceinline__ unsigned xb_add(unsigned* p, unsigned v) { return __hip_atomic_fetch_add(p, v, __ATOMIC_RELAXED, __HIP_MEMORY_SCOPE_AGENT); }
; #define XB_SPIN(cond, bar) do { unsigned _sp = 0; while (cond) { __builtin_amdgcn_s_sleep(1); \
;     if ((++_sp & 255u) == 0u) { if (xb_ld(&(bar)[XB_TMO])) break; if (_sp > XB_SPIN_CAP) { atomicAdd(&(bar)[XB_TMO], 1u); break; } } } } while (0)
; __device__ __forceinline__ void xcd_barrier(const XcdBarrier& b) {
;     ...
;         const unsigned old = xb_add(&bar[XB_XSUB(b.x)], 1u);
;         const unsigned gen = old / nloc;
;         if (old + 1u == (gen + 1u) * nloc) {
;             __builtin_amdgcn_fence(__ATOMIC_RELEASE, "agent");
;             asm volatile("s_waitcnt vmcnt(0)" ::: "memory");
;             const unsigned og = xb_add(&bar[XB_TOP], 1u);
;             const unsigned tg = og / nx;
;             if (og + 1u == (tg + 1u) * nx) xb_add(&bar[XB_TOPGEN], 1u);
;             else XB_SPIN(xb_ld(&bar[XB_TOPGEN]) == tg, bar);
;             __builtin_amdgcn_fence(__ATOMIC_ACQUIRE, "agent");
;             xb_add(&bar[XB_XGEN(b.x)], 1u);
;             asm volatile("s_waitcnt vmcnt(0)" ::: "memory");
;         } else {
;             XB_SPIN(xb_ld(&bar[XB_XGEN(b.x)]) == gen, bar);
;             __builtin_amdgcn_fence(__ATOMIC_ACQUIRE, "agent");
.LBB0_971:
	s_or_b64 exec, exec, s[6:7]
	v_cvt_f32_u32_e32 v5, v3
	s_waitcnt vmcnt(0)
	v_readfirstlane_b32 s2, v4
	v_sub_u32_e32 v4, 0, v3
	v_rcp_iflag_f32_e32 v5, v5
	v_add_u32_e32 v6, s2, v2
	v_mul_f32_e32 v5, 0x4f7ffffe, v5
	v_cvt_u32_f32_e32 v5, v5
	v_mul_lo_u32 v2, v4, v5
	v_mul_hi_u32 v2, v5, v2
	v_add_u32_e32 v2, v5, v2
	v_mul_hi_u32 v2, v6, v2
	v_mul_lo_u32 v4, v2, v3
	v_sub_u32_e32 v4, v6, v4
	v_add_u32_e32 v5, 1, v2
	v_cmp_ge_u32_e32 vcc, v4, v3
	s_nop 1
	v_cndmask_b32_e32 v2, v2, v5, vcc
	v_sub_u32_e32 v5, v4, v3
	v_cndmask_b32_e32 v4, v4, v5, vcc
	v_add_u32_e32 v5, 1, v2
	v_cmp_ge_u32_e32 vcc, v4, v3
	v_add_u32_e32 v4, 1, v6
	s_nop 0
	v_cndmask_b32_e32 v2, v2, v5, vcc
	v_mul_lo_u32 v5, v3, v2
	v_add_u32_e32 v3, v5, v3
	v_cmp_ne_u32_e32 vcc, v4, v3
	s_and_saveexec_b64 s[2:3], vcc
	s_xor_b64 s[2:3], exec, s[2:3]
	s_cbranch_execz .LBB0_985
	s_waitcnt lgkmcnt(0)
	v_mov_b32_e32 v1, 0
	v_readlane_b32 s10, v244, 24
	v_readlane_b32 s11, v244, 25
	s_nop 1
	s_add_u32 s10, s10, 0x7500
	s_addc_u32 s11, s11, 0
	global_load_dword v1, v1, s[10:11] sc1
	s_waitcnt vmcnt(0)
	v_cmp_eq_u32_e32 vcc, v1, v2
	s_and_saveexec_b64 s[6:7], vcc
	s_cbranch_execz .LBB0_984
	v_readlane_b32 s8, v244, 24
	v_readlane_b32 s9, v244, 25
	s_add_u32 s8, s8, 0x4200
	s_addc_u32 s9, s9, 0
	s_mov_b32 s22, 1
	s_mov_b64 s[12:13], 0
	v_mov_b32_e32 v1, 0
	s_branch .LBB0_975

; __device__ __forceinline__ unsigned xb_ld(unsigned* p)              { return __hip_atomic_load(p, __ATOMIC_RELAXED, __HIP_MEMORY_SCOPE_AGENT); }
; __device__ __forceinline__ unsigned xb_add(unsigned* p, unsigned v) { return __hip_atomic_fetch_add(p, v, __ATOMIC_RELAXED, __HIP_MEMORY_SCOPE_AGENT); }
; #define XB_SPIN(cond, bar) do { unsigned _sp = 0; while (cond) { __builtin_amdgcn_s_sleep(1); \
;     if ((++_sp & 255u) == 0u) { if (xb_ld(&(bar)[XB_TMO])) break; if (_sp > XB_SPIN_CAP) { atomicAdd(&(bar)[XB_TMO], 1u); break; } } } } while (0)
; __device__ __forceinline__ void xcd_barrier(const XcdBarrier& b) {
;     ...
;         const unsigned old = xb_add(&bar[XB_XSUB(b.x)], 1u);
;         const unsigned gen = old / nloc;
;         if (old + 1u == (gen + 1u) * nloc) {
;             __builtin_amdgcn_fence(__ATOMIC_RELEASE, "agent");
;             asm volatile("s_waitcnt vmcnt(0)" ::: "memory");
;             const unsigned og = xb_add(&bar[XB_TOP], 1u);
;             const unsigned tg = og / nx;
;             if (og + 1u == (tg + 1u) * nx) xb_add(&bar[XB_TOPGEN], 1u);
;             else XB_SPIN(xb_ld(&bar[XB_TOPGEN]) == tg, bar);
;             __builtin_amdgcn_fence(__ATOMIC_ACQUIRE, "agent");
;             xb_add(&bar[XB_XGEN(b.x)], 1u);
;             asm volatile("s_waitcnt vmcnt(0)" ::: "memory");
;         } else {
;             XB_SPIN(xb_ld(&bar[XB_XGEN(b.x)]) == gen, bar);
;             __builtin_amdgcn_fence(__ATOMIC_ACQUIRE, "agent");
.LBB0_1095:
	s_or_b64 exec, exec, s[6:7]
	v_cvt_f32_u32_e32 v6, v4
	s_waitcnt vmcnt(0)
	v_readfirstlane_b32 s2, v5
	v_sub_u32_e32 v5, 0, v4
	v_rcp_iflag_f32_e32 v6, v6
	v_add_u32_e32 v7, s2, v3
	v_mul_f32_e32 v6, 0x4f7ffffe, v6
	v_cvt_u32_f32_e32 v6, v6
	v_mul_lo_u32 v3, v5, v6
	v_mul_hi_u32 v3, v6, v3
	v_add_u32_e32 v3, v6, v3
	v_mul_hi_u32 v3, v7, v3
	v_mul_lo_u32 v5, v3, v4
	v_sub_u32_e32 v5, v7, v5
	v_add_u32_e32 v6, 1, v3
	v_cmp_ge_u32_e32 vcc, v5, v4
	s_nop 1
	v_cndmask_b32_e32 v3, v3, v6, vcc
	v_sub_u32_e32 v6, v5, v4
	v_cndmask_b32_e32 v5, v5, v6, vcc
	v_add_u32_e32 v6, 1, v3
	v_cmp_ge_u32_e32 vcc, v5, v4
	v_add_u32_e32 v5, 1, v7
	s_nop 0
	v_cndmask_b32_e32 v3, v3, v6, vcc
	v_mul_lo_u32 v6, v4, v3
	v_add_u32_e32 v4, v6, v4
	v_cmp_ne_u32_e32 vcc, v5, v4
	s_and_saveexec_b64 s[2:3], vcc
	s_xor_b64 s[2:3], exec, s[2:3]
	s_cbranch_execz .LBB0_1109
	s_waitcnt lgkmcnt(0)
	v_mov_b32_e32 v2, 0
	v_readlane_b32 s10, v244, 24
	v_readlane_b32 s11, v244, 25
	s_nop 1
	s_add_u32 s10, s10, 0x7500
	s_addc_u32 s11, s11, 0
	global_load_dword v2, v2, s[10:11] sc1
	s_waitcnt vmcnt(0)
	v_cmp_eq_u32_e32 vcc, v2, v3
	s_and_saveexec_b64 s[6:7], vcc
	s_cbranch_execz .LBB0_1108
	v_readlane_b32 s8, v244, 24
	v_readlane_b32 s9, v244, 25
	s_add_u32 s8, s8, 0x4200
	s_addc_u32 s9, s9, 0
	s_mov_b32 s22, 1
	s_mov_b64 s[12:13], 0
	v_mov_b32_e32 v2, 0
	s_branch .LBB0_1099

; __device__ __forceinline__ unsigned xb_ld(unsigned* p)              { return __hip_atomic_load(p, __ATOMIC_RELAXED, __HIP_MEMORY_SCOPE_AGENT); }
; __device__ __forceinline__ unsigned xb_add(unsigned* p, unsigned v) { return __hip_atomic_fetch_add(p, v, __ATOMIC_RELAXED, __HIP_MEMORY_SCOPE_AGENT); }
; #define XB_SPIN(cond, bar) do { unsigned _sp = 0; while (cond) { __builtin_amdgcn_s_sleep(1); \
;     if ((++_sp & 255u) == 0u) { if (xb_ld(&(bar)[XB_TMO])) break; if (_sp > XB_SPIN_CAP) { atomicAdd(&(bar)[XB_TMO], 1u); break; } } } } while (0)
; __device__ __forceinline__ void xcd_barrier(const XcdBarrier& b) {
;     ...
;         const unsigned old = xb_add(&bar[XB_XSUB(b.x)], 1u);
;         const unsigned gen = old / nloc;
;         if (old + 1u == (gen + 1u) * nloc) {
;             __builtin_amdgcn_fence(__ATOMIC_RELEASE, "agent");
;             asm volatile("s_waitcnt vmcnt(0)" ::: "memory");
;             const unsigned og = xb_add(&bar[XB_TOP], 1u);
;             const unsigned tg = og / nx;
;             if (og + 1u == (tg + 1u) * nx) xb_add(&bar[XB_TOPGEN], 1u);
;             else XB_SPIN(xb_ld(&bar[XB_TOPGEN]) == tg, bar);
;             __builtin_amdgcn_fence(__ATOMIC_ACQUIRE, "agent");
;             xb_add(&bar[XB_XGEN(b.x)], 1u);
;             asm volatile("s_waitcnt vmcnt(0)" ::: "memory");
;         } else {
;             XB_SPIN(xb_ld(&bar[XB_XGEN(b.x)]) == gen, bar);
;             __builtin_amdgcn_fence(__ATOMIC_ACQUIRE, "agent");
.LBB0_1437:
	s_or_b64 exec, exec, s[6:7]
	v_cvt_f32_u32_e32 v6, v4
	s_waitcnt vmcnt(0)
	v_readfirstlane_b32 s2, v5
	v_sub_u32_e32 v5, 0, v4
	v_rcp_iflag_f32_e32 v6, v6
	v_add_u32_e32 v7, s2, v3
	v_mul_f32_e32 v6, 0x4f7ffffe, v6
	v_cvt_u32_f32_e32 v6, v6
	v_mul_lo_u32 v3, v5, v6
	v_mul_hi_u32 v3, v6, v3
	v_add_u32_e32 v3, v6, v3
	v_mul_hi_u32 v3, v7, v3
	v_mul_lo_u32 v5, v3, v4
	v_sub_u32_e32 v5, v7, v5
	v_add_u32_e32 v6, 1, v3
	v_cmp_ge_u32_e32 vcc, v5, v4
	s_nop 1
	v_cndmask_b32_e32 v3, v3, v6, vcc
	v_sub_u32_e32 v6, v5, v4
	v_cndmask_b32_e32 v5, v5, v6, vcc
	v_add_u32_e32 v6, 1, v3
	v_cmp_ge_u32_e32 vcc, v5, v4
	v_add_u32_e32 v5, 1, v7
	s_nop 0
	v_cndmask_b32_e32 v3, v3, v6, vcc
	v_mul_lo_u32 v6, v4, v3
	v_add_u32_e32 v4, v6, v4
	v_cmp_ne_u32_e32 vcc, v5, v4
	s_and_saveexec_b64 s[2:3], vcc
	s_xor_b64 s[2:3], exec, s[2:3]
	s_cbranch_execz .LBB0_1453
	s_waitcnt lgkmcnt(0)
	v_mov_b32_e32 v2, 0
	s_add_u32 s10, s54, 0x7500
	s_addc_u32 s11, s55, 0
	global_load_dword v2, v2, s[10:11] sc1
	s_waitcnt vmcnt(0)
	v_cmp_eq_u32_e32 vcc, v2, v3
	s_and_saveexec_b64 s[6:7], vcc
	s_cbranch_execz .LBB0_1452
	s_add_u32 s8, s54, 0x4200
	s_addc_u32 s9, s55, 0
	s_mov_b32 s22, 1
	s_mov_b64 s[12:13], 0
	v_mov_b32_e32 v2, 0
	s_branch .LBB0_1441

; __device__ __forceinline__ unsigned xb_ld(unsigned* p)              { return __hip_atomic_load(p, __ATOMIC_RELAXED, __HIP_MEMORY_SCOPE_AGENT); }
; __device__ __forceinline__ unsigned xb_add(unsigned* p, unsigned v) { return __hip_atomic_fetch_add(p, v, __ATOMIC_RELAXED, __HIP_MEMORY_SCOPE_AGENT); }
; #define XB_SPIN(cond, bar) do { unsigned _sp = 0; while (cond) { __builtin_amdgcn_s_sleep(1); \
;     if ((++_sp & 255u) == 0u) { if (xb_ld(&(bar)[XB_TMO])) break; if (_sp > XB_SPIN_CAP) { atomicAdd(&(bar)[XB_TMO], 1u); break; } } } } while (0)
; __device__ __forceinline__ void xcd_barrier(const XcdBarrier& b) {
;     ...
;         const unsigned old = xb_add(&bar[XB_XSUB(b.x)], 1u);
;         const unsigned gen = old / nloc;
;         if (old + 1u == (gen + 1u) * nloc) {
;             __builtin_amdgcn_fence(__ATOMIC_RELEASE, "agent");
;             asm volatile("s_waitcnt vmcnt(0)" ::: "memory");
;             const unsigned og = xb_add(&bar[XB_TOP], 1u);
;             const unsigned tg = og / nx;
;             if (og + 1u == (tg + 1u) * nx) xb_add(&bar[XB_TOPGEN], 1u);
;             else XB_SPIN(xb_ld(&bar[XB_TOPGEN]) == tg, bar);
;             __builtin_amdgcn_fence(__ATOMIC_ACQUIRE, "agent");
;             xb_add(&bar[XB_XGEN(b.x)], 1u);
;             asm volatile("s_waitcnt vmcnt(0)" ::: "memory");
;         } else {
;             XB_SPIN(xb_ld(&bar[XB_XGEN(b.x)]) == gen, bar);
;             __builtin_amdgcn_fence(__ATOMIC_ACQUIRE, "agent");
.LBB0_1577:
	s_or_b64 exec, exec, s[12:13]
	v_cvt_f32_u32_e32 v6, v4
	s_waitcnt vmcnt(0)
	v_readfirstlane_b32 s2, v5
	v_sub_u32_e32 v5, 0, v4
	v_rcp_iflag_f32_e32 v6, v6
	v_add_u32_e32 v7, s2, v3
	v_mul_f32_e32 v6, 0x4f7ffffe, v6
	v_cvt_u32_f32_e32 v6, v6
	v_mul_lo_u32 v3, v5, v6
	v_mul_hi_u32 v3, v6, v3
	v_add_u32_e32 v3, v6, v3
	v_mul_hi_u32 v3, v7, v3
	v_mul_lo_u32 v5, v3, v4
	v_sub_u32_e32 v5, v7, v5
	v_add_u32_e32 v6, 1, v3
	v_cmp_ge_u32_e32 vcc, v5, v4
	s_nop 1
	v_cndmask_b32_e32 v3, v3, v6, vcc
	v_sub_u32_e32 v6, v5, v4
	v_cndmask_b32_e32 v5, v5, v6, vcc
	v_add_u32_e32 v6, 1, v3
	v_cmp_ge_u32_e32 vcc, v5, v4
	v_add_u32_e32 v5, 1, v7
	s_nop 0
	v_cndmask_b32_e32 v3, v3, v6, vcc
	v_mul_lo_u32 v6, v4, v3
	v_add_u32_e32 v4, v6, v4
	v_cmp_ne_u32_e32 vcc, v5, v4
	s_and_saveexec_b64 s[2:3], vcc
	s_xor_b64 s[2:3], exec, s[2:3]
	s_cbranch_execz .LBB0_1591
	s_waitcnt lgkmcnt(0)
	v_mov_b32_e32 v2, 0
	s_add_u32 s16, s54, 0x7500
	s_addc_u32 s17, s55, 0
	global_load_dword v2, v2, s[16:17] sc1
	s_waitcnt vmcnt(0)
	v_cmp_eq_u32_e32 vcc, v2, v3
	s_and_saveexec_b64 s[12:13], vcc
	s_cbranch_execz .LBB0_1590
	s_add_u32 s14, s54, 0x4200
	s_addc_u32 s15, s55, 0
	s_mov_b32 s28, 1
	s_mov_b64 s[18:19], 0
	v_mov_b32_e32 v2, 0
	s_branch .LBB0_1581
